# in-projection tile order: column tile rotated by 2 for odd row-tile groups so every block gets 4 activation tiles (was 2 or 6)
# baseline (speedup 1.0000x reference)
.LBB0_64:
	s_add_u32 s62, s68, 0x3200000
	s_addc_u32 s63, s69, 0
	s_add_u32 s88, s68, 0x7200000
	s_addc_u32 s89, s69, 0
	s_cmp_lt_i32 s70, 2
	s_cselect_b64 s[0:1], -1, 0
	s_cmp_gt_i32 s71, 1
	s_cselect_b64 s[2:3], -1, 0
	s_and_b64 s[0:1], s[0:1], s[2:3]
	s_andn2_b64 vcc, exec, s[0:1]
	s_cbranch_vccnz .LBB0_174
	s_cmpk_lt_i32 s93, 0x800
	s_cselect_b64 s[0:1], -1, 0
	s_cmpk_gt_i32 s93, 0x7ff
	v_readfirstlane_b32 s10, v186
	s_cbranch_scc1 .LBB0_71
	s_ashr_i32 s2, s93, 31
	s_lshr_b32 s2, s2, 29
	s_add_i32 s4, s93, s2
	s_and_b32 s2, s4, -8
	s_sub_i32 s5, s93, s2
	s_cmp_gt_i32 s5, -1
	s_cbranch_scc0 .LBB0_68
	s_lshl_b32 s6, s5, 8
	s_cbranch_execz .LBB0_69
	s_branch .LBB0_70
	s_nop 0
	s_nop 0
	s_nop 0
	s_nop 0
	s_nop 0
	s_nop 0
	s_nop 0
	s_nop 0
	s_nop 0
	s_nop 0
	s_nop 0
	s_nop 0
	s_nop 0
	s_nop 0
	s_nop 0
	s_nop 0
	s_nop 0
	s_nop 0
	s_nop 0
	s_nop 0
	s_nop 0
	s_nop 0
	s_nop 0
	s_nop 0

.LBB0_70:
	s_ashr_i32 s2, s4, 3
	s_add_i32 s2, s6, s2
	s_ashr_i32 s3, s2, 31
	s_lshr_b32 s3, s3, 25
	s_add_i32 s3, s2, s3
	s_ashr_i32 s4, s3, 7
	s_and_b32 s3, s3, 0xffffff80
	s_sub_i32 s2, s2, s3
	s_bfe_i32 s3, s2, 0x80000
	s_bfe_u32 s3, s3, 0x3000c
	s_add_i32 s3, s2, s3
	s_bfe_i32 s5, s3, 0x80000
	s_and_b32 s3, s3, 0xf8
	s_sub_i32 s2, s2, s3
	s_lshl_b32 s4, s4, 3
	s_sext_i32_i16 s5, s5
	s_sext_i32_i8 s2, s2
	s_add_i32 s22, s4, s2
	s_ashr_i32 s4, s5, 3
	s_bfe_u32 s2, s22, 0x10003
	s_lshl_b32 s2, s2, 1
	s_add_i32 s4, s4, s2
	s_and_b32 s4, s4, 15

.LBB0_83:
	s_bfe_u32 s17, s16, 0x10003
	s_lshl_b32 s17, s17, 1
	s_add_i32 s14, s14, s17
	s_and_b32 s14, s14, 15
	s_ashr_i32 s17, s16, 31
	s_lshl_b64 s[18:19], s[16:17], 19
	s_add_u32 s18, s62, s18
	s_addc_u32 s19, s63, s19
	s_and_b64 s[20:21], s[2:3], exec
	s_cselect_b32 s5, s19, s1
	s_cselect_b32 s17, s18, s0
	s_ashr_i32 s15, s14, 31
	s_lshl_b64 s[20:21], s[14:15], 19
	s_add_u32 s20, s68, s20
	s_addc_u32 s21, s69, s21
	s_and_b64 s[26:27], s[2:3], exec
	s_cselect_b32 s15, s21, s25
	s_cselect_b32 s23, s20, s24
	s_add_u32 s0, s0, 0x40080
	s_addc_u32 s1, s1, 0
	s_add_u32 s42, s24, 0x100
	v_mov_b32_e32 v0, 0
	s_addc_u32 s43, s25, 0
	s_mov_b32 s44, -2
	v_mov_b32_e32 v1, v0
	v_mov_b32_e32 v2, v0
	v_mov_b32_e32 v3, v0
	v_mov_b32_e32 v4, v0
	v_mov_b32_e32 v5, v0
	v_mov_b32_e32 v6, v0
	v_mov_b32_e32 v7, v0
	v_mov_b32_e32 v16, v0
	v_mov_b32_e32 v17, v0
	v_mov_b32_e32 v18, v0
	v_mov_b32_e32 v19, v0
	v_mov_b32_e32 v20, v0
	v_mov_b32_e32 v21, v0
	v_mov_b32_e32 v22, v0
	v_mov_b32_e32 v23, v0
	v_mov_b32_e32 v32, v0
	v_mov_b32_e32 v33, v0
	v_mov_b32_e32 v34, v0
	v_mov_b32_e32 v35, v0
	v_mov_b32_e32 v36, v0
	v_mov_b32_e32 v37, v0
	v_mov_b32_e32 v38, v0
	v_mov_b32_e32 v39, v0
	v_mov_b32_e32 v56, v0
	v_mov_b32_e32 v57, v0
	v_mov_b32_e32 v58, v0
	v_mov_b32_e32 v59, v0
	v_mov_b32_e32 v60, v0
	v_mov_b32_e32 v61, v0
	v_mov_b32_e32 v62, v0
	v_mov_b32_e32 v63, v0
	v_mov_b32_e32 v8, v0
	v_mov_b32_e32 v9, v0
	v_mov_b32_e32 v10, v0
	v_mov_b32_e32 v11, v0
	v_mov_b32_e32 v12, v0
	v_mov_b32_e32 v13, v0
	v_mov_b32_e32 v14, v0
	v_mov_b32_e32 v15, v0
	v_mov_b32_e32 v24, v0
	v_mov_b32_e32 v25, v0
	v_mov_b32_e32 v26, v0
	v_mov_b32_e32 v27, v0
	v_mov_b32_e32 v28, v0
	v_mov_b32_e32 v29, v0
	v_mov_b32_e32 v30, v0
	v_mov_b32_e32 v31, v0
	v_mov_b32_e32 v40, v0
	v_mov_b32_e32 v41, v0
	v_mov_b32_e32 v42, v0
	v_mov_b32_e32 v43, v0
	v_mov_b32_e32 v44, v0
	v_mov_b32_e32 v45, v0
	v_mov_b32_e32 v46, v0
	v_mov_b32_e32 v47, v0
	v_mov_b32_e32 v72, v0
	v_mov_b32_e32 v73, v0
	v_mov_b32_e32 v74, v0
	v_mov_b32_e32 v75, v0
	v_mov_b32_e32 v76, v0
	v_mov_b32_e32 v77, v0
	v_mov_b32_e32 v78, v0
	v_mov_b32_e32 v79, v0
	v_mov_b32_e32 v80, v0
	v_mov_b32_e32 v81, v0
	v_mov_b32_e32 v82, v0
	v_mov_b32_e32 v83, v0
	v_mov_b32_e32 v84, v0
	v_mov_b32_e32 v85, v0
	v_mov_b32_e32 v86, v0
	v_mov_b32_e32 v87, v0
	v_mov_b32_e32 v96, v0
	v_mov_b32_e32 v97, v0
	v_mov_b32_e32 v98, v0
	v_mov_b32_e32 v99, v0
	v_mov_b32_e32 v100, v0
	v_mov_b32_e32 v101, v0
	v_mov_b32_e32 v102, v0
	v_mov_b32_e32 v103, v0
	v_mov_b32_e32 v112, v0
	v_mov_b32_e32 v113, v0
	v_mov_b32_e32 v114, v0
	v_mov_b32_e32 v115, v0
	v_mov_b32_e32 v116, v0
	v_mov_b32_e32 v117, v0
	v_mov_b32_e32 v118, v0
	v_mov_b32_e32 v119, v0
	v_mov_b32_e32 v128, v0
	v_mov_b32_e32 v129, v0
	v_mov_b32_e32 v130, v0
	v_mov_b32_e32 v131, v0
	v_mov_b32_e32 v132, v0
	v_mov_b32_e32 v133, v0
	v_mov_b32_e32 v134, v0
	v_mov_b32_e32 v135, v0
	v_mov_b32_e32 v88, v0
	v_mov_b32_e32 v89, v0
	v_mov_b32_e32 v90, v0
	v_mov_b32_e32 v91, v0
	v_mov_b32_e32 v92, v0
	v_mov_b32_e32 v93, v0
	v_mov_b32_e32 v94, v0
	v_mov_b32_e32 v95, v0
	v_mov_b32_e32 v104, v0
	v_mov_b32_e32 v105, v0
	v_mov_b32_e32 v106, v0
	v_mov_b32_e32 v107, v0
	v_mov_b32_e32 v108, v0
	v_mov_b32_e32 v109, v0
	v_mov_b32_e32 v110, v0
	v_mov_b32_e32 v111, v0
	v_mov_b32_e32 v120, v0
	v_mov_b32_e32 v121, v0
	v_mov_b32_e32 v122, v0
	v_mov_b32_e32 v123, v0
	v_mov_b32_e32 v124, v0
	v_mov_b32_e32 v125, v0
	v_mov_b32_e32 v126, v0
	v_mov_b32_e32 v127, v0
	v_mov_b32_e32 v136, v0
	v_mov_b32_e32 v137, v0
	v_mov_b32_e32 v138, v0
	v_mov_b32_e32 v139, v0
	v_mov_b32_e32 v140, v0
	v_mov_b32_e32 v141, v0
	v_mov_b32_e32 v142, v0
	v_mov_b32_e32 v143, v0
